# generic attention epilogues (modes 1/2, ctx): dwordx2 stores -> dwordx4 via v_permlane32_swap
# speedup vs baseline: 1.0120x; 1.0018x over previous
; DI void attn_item(const Params& p, int layer, int item, char* smem) {
;     ...
;   float l_tot = lacc[0];
;   if (hasSink) l_tot += __builtin_amdgcn_exp2f(sinkv * LOG2E - m_fix);
;   float inv = 1.f / l_tot;
;   int T = (mode == 3) ? (TLAT + b * 256 + (qpos - 4096)) : (b * 4096 + qpos);
;   u16* od = p.O + (size_t)T * LDK + head16 * 64;
; #pragma unroll
;   for (int g = 0; g < 4; ++g) {
;     int d0 = 8 * g + 4 * h;
;     *(uint2*)(od + d0) = make_uint2(pack_bf16(o0[4 * g] * inv, o0[4 * g + 1] * inv), pack_bf16(o0[4 * g + 2] * inv, o0[4 * g + 3] * inv));
;     *(uint2*)(od + 32 + d0) = make_uint2(pack_bf16(o1[4 * g] * inv, o1[4 * g + 1] * inv), pack_bf16(o1[4 * g + 2] * inv, o1[4 * g + 3] * inv));
;   }
.LBB0_485:
	s_mov_b32 s0, 0x3fb8aa3b
	v_fma_f32 v0, v174, s0, -v165
	v_exp_f32_e32 v0, v0
	v_readlane_b32 s0, v254, 54
	v_readlane_b32 s1, v254, 55
	s_lshl_b32 s2, s16, 7
	v_add_f32_e32 v0, v0, v64
	v_cndmask_b32_e64 v0, v64, v0, s[0:1]
	v_div_scale_f32 v3, s[0:1], v0, v0, 1.0
	v_rcp_f32_e32 v4, v3
	v_readlane_b32 s0, v252, 35
	v_readlane_b32 s1, v252, 36
	s_mov_b32 s3, s1
	v_fma_f32 v5, -v3, v4, 1.0
	v_fmac_f32_e32 v4, v5, v4
	v_div_scale_f32 v5, vcc, 1.0, v0, 1.0
	v_mul_f32_e32 v6, v5, v4
	v_fma_f32 v7, -v3, v6, v5
	v_fmac_f32_e32 v6, v7, v4
	v_fma_f32 v3, -v3, v6, v5
	v_div_fmas_f32 v3, v3, v4, v6
	v_div_fixup_f32 v4, v3, v0, 1.0
	v_ashrrev_i32_e32 v3, 31, v2
	v_lshlrev_b64 v[2:3], 11, v[2:3]
	v_lshl_add_u64 v[2:3], s[90:91], 0, v[2:3]
	v_lshl_add_u64 v[2:3], v[2:3], 0, s[2:3]
	v_lshlrev_b32_e32 v0, 4, v175
	v_lshl_add_u64 v[2:3], v[2:3], 0, v[0:1]
	v_pk_mul_f32 v[6:7], v[32:33], v[4:5] op_sel_hi:[1,0]
	v_pk_mul_f32 v[8:9], v[34:35], v[4:5] op_sel_hi:[1,0]
	v_pk_mul_f32 v[10:11], v[36:37], v[4:5] op_sel_hi:[1,0]
	v_pk_mul_f32 v[12:13], v[38:39], v[4:5] op_sel_hi:[1,0]
	v_cvt_pk_bf16_f32 v6, v6, v7
	v_cvt_pk_bf16_f32 v7, v8, v9
	v_cvt_pk_bf16_f32 v8, v10, v11
	v_cvt_pk_bf16_f32 v9, v12, v13
	s_nop 1
	v_permlane32_swap_b32_e32 v6, v8
	v_permlane32_swap_b32_e32 v7, v9
	global_store_dwordx4 v[2:3], v[6:9], off
	s_nop 1
	v_pk_mul_f32 v[6:7], v[40:41], v[4:5] op_sel_hi:[1,0]
	v_pk_mul_f32 v[8:9], v[42:43], v[4:5] op_sel_hi:[1,0]
	v_pk_mul_f32 v[10:11], v[44:45], v[4:5] op_sel_hi:[1,0]
	v_pk_mul_f32 v[12:13], v[46:47], v[4:5] op_sel_hi:[1,0]
	v_cvt_pk_bf16_f32 v6, v6, v7
	v_cvt_pk_bf16_f32 v7, v8, v9
	v_cvt_pk_bf16_f32 v8, v10, v11
	v_cvt_pk_bf16_f32 v9, v12, v13
	s_nop 1
	v_permlane32_swap_b32_e32 v6, v8
	v_permlane32_swap_b32_e32 v7, v9
	global_store_dwordx4 v[2:3], v[6:9], off offset:32
	s_nop 1
	v_pk_mul_f32 v[6:7], v[16:17], v[4:5] op_sel_hi:[1,0]
	v_pk_mul_f32 v[8:9], v[18:19], v[4:5] op_sel_hi:[1,0]
	v_pk_mul_f32 v[10:11], v[20:21], v[4:5] op_sel_hi:[1,0]
	v_pk_mul_f32 v[12:13], v[22:23], v[4:5] op_sel_hi:[1,0]
	v_cvt_pk_bf16_f32 v6, v6, v7
	v_cvt_pk_bf16_f32 v7, v8, v9
	v_cvt_pk_bf16_f32 v8, v10, v11
	v_cvt_pk_bf16_f32 v9, v12, v13
	s_nop 1
	v_permlane32_swap_b32_e32 v6, v8
	v_permlane32_swap_b32_e32 v7, v9
	global_store_dwordx4 v[2:3], v[6:9], off offset:64
	s_nop 1
	v_pk_mul_f32 v[6:7], v[24:25], v[4:5] op_sel_hi:[1,0]
	v_pk_mul_f32 v[8:9], v[26:27], v[4:5] op_sel_hi:[1,0]
	v_pk_mul_f32 v[10:11], v[28:29], v[4:5] op_sel_hi:[1,0]
	v_pk_mul_f32 v[12:13], v[30:31], v[4:5] op_sel_hi:[1,0]
	v_cvt_pk_bf16_f32 v6, v6, v7
	v_cvt_pk_bf16_f32 v7, v8, v9
	v_cvt_pk_bf16_f32 v8, v10, v11
	v_cvt_pk_bf16_f32 v9, v12, v13
	s_nop 1
	v_permlane32_swap_b32_e32 v6, v8
	v_permlane32_swap_b32_e32 v7, v9
	v_writelane_b32 v252, s0, 35
	v_writelane_b32 v252, s1, 36
	global_store_dwordx4 v[2:3], v[6:9], off offset:96
	s_mov_b64 s[0:1], 0

; DI void attn_item(const Params& p, int layer, int item, char* smem) {
;     ...
;   float l_tot = lacc[0];
;   if (hasSink) l_tot += __builtin_amdgcn_exp2f(sinkv * LOG2E - m_fix);
;   float inv = 1.f / l_tot;
;   int T = (mode == 3) ? (TLAT + b * 256 + (qpos - 4096)) : (b * 4096 + qpos);
;   u16* od = p.O + (size_t)T * LDK + head16 * 64;
; #pragma unroll
;   for (int g = 0; g < 4; ++g) {
;     int d0 = 8 * g + 4 * h;
;     *(uint2*)(od + d0) = make_uint2(pack_bf16(o0[4 * g] * inv, o0[4 * g + 1] * inv), pack_bf16(o0[4 * g + 2] * inv, o0[4 * g + 3] * inv));
;     *(uint2*)(od + 32 + d0) = make_uint2(pack_bf16(o1[4 * g] * inv, o1[4 * g + 1] * inv), pack_bf16(o1[4 * g + 2] * inv, o1[4 * g + 3] * inv));
;   }
.LBB0_579:
	s_mov_b32 s0, 0x3fb8aa3b
	v_fma_f32 v0, v174, s0, -v165
	v_exp_f32_e32 v0, v0
	v_readlane_b32 s0, v254, 35
	v_readlane_b32 s1, v254, 36
	s_add_i32 s14, s14, s55
	v_add_f32_e32 v0, v0, v64
	v_cndmask_b32_e64 v0, v64, v0, s[0:1]
	v_div_scale_f32 v3, s[0:1], v0, v0, 1.0
	v_rcp_f32_e32 v4, v3
	v_readlane_b32 s0, v254, 31
	s_lshl_b32 s0, s0, 6
	s_ashr_i32 s1, s0, 31
	v_fma_f32 v5, -v3, v4, 1.0
	v_fmac_f32_e32 v4, v5, v4
	v_div_scale_f32 v5, vcc, 1.0, v0, 1.0
	v_mul_f32_e32 v6, v5, v4
	v_fma_f32 v7, -v3, v6, v5
	v_fmac_f32_e32 v6, v7, v4
	v_fma_f32 v3, -v3, v6, v5
	v_div_fmas_f32 v3, v3, v4, v6
	v_div_fixup_f32 v4, v3, v0, 1.0
	v_ashrrev_i32_e32 v3, 31, v2
	v_lshlrev_b64 v[2:3], 11, v[2:3]
	v_lshl_add_u64 v[2:3], s[90:91], 0, v[2:3]
	v_lshl_add_u64 v[2:3], s[0:1], 1, v[2:3]
	v_lshlrev_b32_e32 v0, 4, v175
	v_lshl_add_u64 v[2:3], v[2:3], 0, v[0:1]
	v_pk_mul_f32 v[6:7], v[32:33], v[4:5] op_sel_hi:[1,0]
	v_pk_mul_f32 v[8:9], v[34:35], v[4:5] op_sel_hi:[1,0]
	v_pk_mul_f32 v[10:11], v[36:37], v[4:5] op_sel_hi:[1,0]
	v_pk_mul_f32 v[12:13], v[38:39], v[4:5] op_sel_hi:[1,0]
	v_cvt_pk_bf16_f32 v6, v6, v7
	v_cvt_pk_bf16_f32 v7, v8, v9
	v_cvt_pk_bf16_f32 v8, v10, v11
	v_cvt_pk_bf16_f32 v9, v12, v13
	s_nop 1
	v_permlane32_swap_b32_e32 v6, v8
	v_permlane32_swap_b32_e32 v7, v9
	global_store_dwordx4 v[2:3], v[6:9], off
	s_nop 1
	v_pk_mul_f32 v[6:7], v[40:41], v[4:5] op_sel_hi:[1,0]
	v_pk_mul_f32 v[8:9], v[42:43], v[4:5] op_sel_hi:[1,0]
	v_pk_mul_f32 v[10:11], v[44:45], v[4:5] op_sel_hi:[1,0]
	v_pk_mul_f32 v[12:13], v[46:47], v[4:5] op_sel_hi:[1,0]
	v_cvt_pk_bf16_f32 v6, v6, v7
	v_cvt_pk_bf16_f32 v7, v8, v9
	v_cvt_pk_bf16_f32 v8, v10, v11
	v_cvt_pk_bf16_f32 v9, v12, v13
	s_nop 1
	v_permlane32_swap_b32_e32 v6, v8
	v_permlane32_swap_b32_e32 v7, v9
	global_store_dwordx4 v[2:3], v[6:9], off offset:32
	s_nop 1
	v_pk_mul_f32 v[6:7], v[16:17], v[4:5] op_sel_hi:[1,0]
	v_pk_mul_f32 v[8:9], v[18:19], v[4:5] op_sel_hi:[1,0]
	v_pk_mul_f32 v[10:11], v[20:21], v[4:5] op_sel_hi:[1,0]
	v_pk_mul_f32 v[12:13], v[22:23], v[4:5] op_sel_hi:[1,0]
	v_cvt_pk_bf16_f32 v6, v6, v7
	v_cvt_pk_bf16_f32 v7, v8, v9
	v_cvt_pk_bf16_f32 v8, v10, v11
	v_cvt_pk_bf16_f32 v9, v12, v13
	s_nop 1
	v_permlane32_swap_b32_e32 v6, v8
	v_permlane32_swap_b32_e32 v7, v9
	global_store_dwordx4 v[2:3], v[6:9], off offset:64
	s_nop 1
	v_pk_mul_f32 v[6:7], v[24:25], v[4:5] op_sel_hi:[1,0]
	v_pk_mul_f32 v[8:9], v[26:27], v[4:5] op_sel_hi:[1,0]
	v_pk_mul_f32 v[10:11], v[28:29], v[4:5] op_sel_hi:[1,0]
	v_pk_mul_f32 v[12:13], v[30:31], v[4:5] op_sel_hi:[1,0]
	v_cvt_pk_bf16_f32 v6, v6, v7
	v_cvt_pk_bf16_f32 v7, v8, v9
	v_cvt_pk_bf16_f32 v8, v10, v11
	v_cvt_pk_bf16_f32 v9, v12, v13
	s_nop 1
	v_permlane32_swap_b32_e32 v6, v8
	v_permlane32_swap_b32_e32 v7, v9
	s_cmp_gt_i32 s14, 63
	global_store_dwordx4 v[2:3], v[6:9], off offset:96
	s_cbranch_scc1 .LBB0_823
